# MLA up-projection tile epilogue (epi_slot) stores widened to 16-byte via v_permlane32_swap; counted vmcnt adjusted
# baseline (speedup 1.0000x reference)
; template <bool SWAP>
; DI void gemm_mainloop(const bf16_t* __restrict__ Xb, long x_slab, int ldx, const bf16_t* __restrict__ Wb, int K, char* smem,
;                       f32x16 (&acc)[2][2]) {
;   const int tid = otid(), lane = tid & 63, wave = tid >> 6, r = lane & 31, h = lane >> 5;
;   const int wm = wave >> 1, wn = wave & 1;
;   const int nkt = K >> 6;
;   const int lrow = tid >> 3, lseg = tid & 7;
;   const bf16_t* xg = Xb + (long)lrow * ldx + lseg * 8;
;   const bf16_t* wg = Wb + (long)lrow * K + lseg * 8;
;   const int lds_off = lrow * G_ROW + lseg * 16;
;   uint4 xr[4], wr[2];
; #pragma unroll
;   for (int j = 0; j < 4; ++j) xr[j] = *(const uint4*)(xg + (long)j * 64 * ldx);
; #pragma unroll
;   for (int j = 0; j < 2; ++j) wr[j] = *(const uint4*)(wg + (long)j * 64 * K);
; #pragma unroll
;   for (int j = 0; j < 4; ++j) *(uint4*)(smem + lds_off + j * 64 * G_ROW) = xr[j];
; #pragma unroll
;   for (int j = 0; j < 2; ++j) *(uint4*)(smem + G_XS + lds_off + j * 64 * G_ROW) = wr[j];
;   __syncthreads();
;   const int xs_off = (wm * 64 + r) * G_ROW + h * 16;
;   const int ws_off = G_XS + (wn * 64 + r) * G_ROW + h * 16;
;   for (int kt = 0; kt < nkt; ++kt) {
;     const char* cur = smem + (kt & 1) * G_STAGE;
;     char* nxt = smem + ((kt + 1) & 1) * G_STAGE;
;     const bool more = (kt + 1 < nkt);
;     if (more) {
;       const bf16_t* xg2 = xg + (long)(kt + 1) * x_slab;
;       const bf16_t* wg2 = wg + (kt + 1) * 64;
; #pragma unroll
;       for (int j = 0; j < 4; ++j) xr[j] = *(const uint4*)(xg2 + (long)j * 64 * ldx);
; #pragma unroll
;       for (int j = 0; j < 2; ++j) wr[j] = *(const uint4*)(wg2 + (long)j * 64 * K);
;     }
; #pragma unroll
;     for (int ks = 0; ks < 4; ++ks) {
;       bf16x8 xf[2], wf[2];
;       xf[0] = *(const bf16x8*)(cur + xs_off + ks * 32);
;       xf[1] = *(const bf16x8*)(cur + xs_off + 32 * G_ROW + ks * 32);
;       wf[0] = *(const bf16x8*)(cur + ws_off + ks * 32);
;       wf[1] = *(const bf16x8*)(cur + ws_off + 32 * G_ROW + ks * 32);
; #pragma unroll
;       for (int nb = 0; nb < 2; ++nb)
; #pragma unroll
;         for (int tb = 0; tb < 2; ++tb) {
;           if (SWAP) acc[nb][tb] = MFMA(wf[nb], xf[tb], acc[nb][tb]);
;           else      acc[nb][tb] = MFMA(xf[tb], wf[nb], acc[nb][tb]);
;         }
;     }
;     if (more) {
; #pragma unroll
;       for (int j = 0; j < 4; ++j) *(uint4*)(nxt + lds_off + j * 64 * G_ROW) = xr[j];
.LBB0_563:
	s_cmpk_gt_i32 s40, 0x2ff
	s_mov_b64 s[0:1], -1
	s_cbranch_scc0 .LBB0_574
	s_and_b32 s36, s40, 3
	s_and_b32 s0, s31, 0xff00
	s_lshl_b32 s1, s36, 15
	v_mov_b32_e32 v74, v228
	v_mov_b32_e32 v0, v228
	s_add_u32 s2, s9, s1
	s_addc_u32 s3, s10, 0
	s_lshl_b32 s1, s0, 7
	v_readlane_b32 s4, v251, 21
	v_bfe_u32 v83, v0, 6, 1
	s_add_u32 s4, s4, s1
	v_readlane_b32 s1, v251, 22
	v_ashrrev_i32_e32 v0, 1, v0
	s_addc_u32 s5, s1, 0
	v_and_b32_e32 v0, 0xffffffc0, v0
	s_cmp_lt_u32 s36, 2
	v_add_u32_e32 v82, s0, v0
	s_mov_b64 s[0:1], -1
	s_cbranch_scc0 .LBB0_571
	v_mov_b32_e32 v28, v228
	s_mov_b32 s0, 0x802000
	v_ashrrev_i32_e32 v26, 3, v28
	v_ashrrev_i32_e32 v27, 31, v26
	s_waitcnt lgkmcnt(0)
	v_lshlrev_b64 v[2:3], 7, v[26:27]
	v_lshlrev_b32_e32 v0, 4, v28
	v_lshl_add_u64 v[2:3], s[4:5], 0, v[2:3]
	v_and_b32_e32 v0, 0x70, v0
	v_lshl_add_u64 v[80:81], v[2:3], 0, v[0:1]
	v_lshlrev_b64 v[2:3], 8, v[26:27]
	v_lshl_add_u64 v[2:3], s[2:3], 0, v[2:3]
	v_lshl_add_u64 v[100:101], v[2:3], 0, v[0:1]
	v_add_co_u32_e32 v2, vcc, s44, v80
	v_and_b32_e32 v27, 31, v28
	s_nop 0
	v_addc_co_u32_e32 v3, vcc, 0, v81, vcc
	v_add_co_u32_e32 v6, vcc, s43, v80
	v_lshrrev_b32_e32 v29, 1, v28
	s_nop 0
	v_addc_co_u32_e32 v7, vcc, 0, v81, vcc
	v_add_co_u32_e32 v18, vcc, s42, v80
	global_load_dwordx4 v[2:5], v[2:3], off
	s_nop 0
	global_load_dwordx4 v[6:9], v[6:7], off
	v_addc_co_u32_e32 v19, vcc, 0, v81, vcc
	v_add_co_u32_e32 v102, vcc, s43, v100
	global_load_dwordx4 v[10:13], v[80:81], off
	global_load_dwordx4 v[14:17], v[100:101], off
	v_addc_co_u32_e32 v103, vcc, 0, v101, vcc
	global_load_dwordx4 v[18:21], v[18:19], off
	s_nop 0
	global_load_dwordx4 v[22:25], v[102:103], off
	v_and_b32_e32 v28, 0x5f, v28
	v_mul_lo_u32 v26, v26, s33
	v_and_b32_e32 v30, 16, v29
	v_mul_u32_u24_e32 v28, 0x90, v28
	v_add3_u32 v0, v26, v0, 0
	v_add3_u32 v75, 0, v28, v30
	v_and_or_b32 v74, v74, 31, v82
	s_lshl_b32 s34, s36, 1
	s_waitcnt vmcnt(0)
	ds_write_b128 v0, v[10:13]
	ds_write_b128 v0, v[14:17] offset:36864
	ds_write_b128 v0, v[2:5] offset:9216
	ds_write_b128 v0, v[6:9] offset:18432
	ds_write_b128 v0, v[18:21] offset:27648
	ds_write_b128 v0, v[22:25] offset:46080
	s_waitcnt lgkmcnt(0)
	s_barrier
	ds_read_b128 v[2:5], v75 offset:36864
	v_and_or_b32 v6, v29, s46, v27
	v_mul_lo_u32 v6, v6, s33
	v_add3_u32 v112, 0, v6, v30
	ds_read_b128 v[6:9], v112
	ds_read_b128 v[66:69], v112 offset:32
	ds_read_b128 v[70:73], v75 offset:36896
	ds_read_b128 v[10:13], v112 offset:4608
	ds_read_b128 v[76:79], v112 offset:4640
	s_waitcnt lgkmcnt(4)
	v_mfma_f32_32x32x16_bf16 v[50:65], v[2:5], v[6:9], 0
	s_waitcnt lgkmcnt(1)
	v_mfma_f32_32x32x16_bf16 v[18:33], v[2:5], v[10:13], 0
	ds_read_b128 v[2:5], v75 offset:41472
	ds_read_b128 v[84:87], v75 offset:41504
	s_waitcnt lgkmcnt(1)
	v_mfma_f32_32x32x16_bf16 v[34:49], v[2:5], v[6:9], 0
	v_mfma_f32_32x32x16_bf16 v[2:17], v[2:5], v[10:13], 0
	v_mfma_f32_32x32x16_bf16 v[50:65], v[70:73], v[66:69], v[50:65]
	v_mfma_f32_32x32x16_bf16 v[18:33], v[70:73], v[76:79], v[18:33]
	s_waitcnt lgkmcnt(0)
	v_mfma_f32_32x32x16_bf16 v[34:49], v[84:87], v[66:69], v[34:49]
	v_mfma_f32_32x32x16_bf16 v[2:17], v[84:87], v[76:79], v[2:17]
	ds_read_b128 v[66:69], v75 offset:36928
	ds_read_b128 v[70:73], v112 offset:64
	ds_read_b128 v[76:79], v112 offset:96
	ds_read_b128 v[84:87], v75 offset:36960
	ds_read_b128 v[88:91], v112 offset:4672
	ds_read_b128 v[92:95], v112 offset:4704
	s_waitcnt lgkmcnt(4)
	v_mfma_f32_32x32x16_bf16 v[50:65], v[66:69], v[70:73], v[50:65]
	s_waitcnt lgkmcnt(1)
	v_mfma_f32_32x32x16_bf16 v[18:33], v[66:69], v[88:91], v[18:33]
	ds_read_b128 v[66:69], v75 offset:41536
	ds_read_b128 v[96:99], v75 offset:41568
	v_add_u32_e32 v75, 0xd800, v75
	s_waitcnt lgkmcnt(1)
	v_mfma_f32_32x32x16_bf16 v[34:49], v[66:69], v[70:73], v[34:49]
	v_mfma_f32_32x32x16_bf16 v[2:17], v[66:69], v[88:91], v[2:17]
	v_add_co_u32_e32 v66, vcc, s45, v80
	s_nop 1
	v_addc_co_u32_e32 v67, vcc, 0, v81, vcc
	v_add_co_u32_e32 v70, vcc, s0, v80
	s_mov_b32 s0, 0x804000
	s_nop 0
	v_addc_co_u32_e32 v71, vcc, 0, v81, vcc
	v_add_co_u32_e32 v88, vcc, s0, v80
	s_mov_b32 s0, 0x806000
	s_nop 0
	v_addc_co_u32_e32 v89, vcc, 0, v81, vcc
	v_add_co_u32_e32 v80, vcc, s0, v80
	v_mfma_f32_32x32x16_bf16 v[50:65], v[84:87], v[76:79], v[50:65]
	s_nop 0
	v_addc_co_u32_e32 v81, vcc, 0, v81, vcc
	v_readlane_b32 s0, v251, 23
	v_readlane_b32 s1, v251, 24
	v_mfma_f32_32x32x16_bf16 v[18:33], v[84:87], v[92:95], v[18:33]
	global_load_dwordx4 v[66:69], v[66:67], off
	s_nop 0
	global_load_dwordx4 v[70:73], v[70:71], off
	s_nop 0
	global_load_dwordx4 v[84:87], v[88:89], off
	s_nop 0
	global_load_dwordx4 v[88:91], v[80:81], off
	v_add_u32_e32 v80, 0xd800, v0
	v_add_u32_e32 v81, 0x16800, v0
	s_waitcnt lgkmcnt(0)
	v_mfma_f32_32x32x16_bf16 v[34:49], v[96:99], v[76:79], v[34:49]
	global_load_dwordx4 v[76:79], v[100:101], off offset:128
	s_nop 0
	global_load_dwordx4 v[100:103], v[102:103], off offset:128
	s_waitcnt vmcnt(5)
	ds_write_b128 v0, v[66:69] offset:55296
	s_waitcnt vmcnt(4)
	ds_write_b128 v0, v[70:73] offset:64512
	s_waitcnt vmcnt(3)
	ds_write_b128 v80, v[84:87] offset:18432
	s_waitcnt vmcnt(2)
	ds_write_b128 v80, v[88:91] offset:27648
	s_waitcnt vmcnt(1)
	ds_write_b128 v81, v[76:79]
	s_waitcnt vmcnt(0)
	ds_write_b128 v81, v[100:103] offset:9216
	v_mfma_f32_32x32x16_bf16 v[2:17], v[96:99], v[92:95], v[2:17]
	s_waitcnt lgkmcnt(0)
	s_barrier
; template <bool SWAP>
; DI void gemm_mainloop(const bf16_t* __restrict__ Xb, long x_slab, int ldx, const bf16_t* __restrict__ Wb, int K, char* smem,
;                       f32x16 (&acc)[2][2]) {
;     ...
;     for (int ks = 0; ks < 4; ++ks) {
;       bf16x8 xf[2], wf[2];
;       xf[0] = *(const bf16x8*)(cur + xs_off + ks * 32);
;       xf[1] = *(const bf16x8*)(cur + xs_off + 32 * G_ROW + ks * 32);
;       wf[0] = *(const bf16x8*)(cur + ws_off + ks * 32);
;       wf[1] = *(const bf16x8*)(cur + ws_off + 32 * G_ROW + ks * 32);
; #pragma unroll
;       for (int nb = 0; nb < 2; ++nb)
; #pragma unroll
;         for (int tb = 0; tb < 2; ++tb) {
;           if (SWAP) acc[nb][tb] = MFMA(wf[nb], xf[tb], acc[nb][tb]);
;           else      acc[nb][tb] = MFMA(xf[tb], wf[nb], acc[nb][tb]);
;         }
;     }
; DI void epi_slot(f32x16 (&acc)[2][2], bf16_t* dst  , int tok0  , const float* norm_gain,
;                  int rope, const float2* tab, float* ssq_out, const float (&rs)[2], unsigned* kmax_out = nullptr) {
;     ...
;   for (int tb = 0; tb < 2; ++tb) {
;     const int tok = tok0 + tb * 32 + r;
;     float sc = rs[tb];
;     if (norm_gain || ssq_out) {
;       float ss = 0.f;
; #pragma unroll
;       for (int nb = 0; nb < 2; ++nb)
; #pragma unroll
;         for (int i = 0; i < 16; ++i) ss += acc[nb][tb][i] * acc[nb][tb][i];
;       ss += xhalf(ss);
;       if (ssq_out && h == 0) ssq_out[(size_t)tok * 8] = ss;
;       if (norm_gain) {
;         const float rstd = frsq(ss * (1.f / 64.f) + EPS);
; #pragma unroll
;         for (int nb = 0; nb < 2; ++nb)
; #pragma unroll
;           for (int i = 0; i < 16; ++i) acc[nb][tb][i] *= rstd * norm_gain[nb * 32 + crow(i, h)];
;       }
;     }
;     if (rope) {
;       const int s = tok & (SEQ - 1);
; #pragma unroll
;       for (int nb = 0; nb < 2; ++nb) {
;         const int pos = (rope == 2) ? s : (nb == 0 ? (s >> 6) : (s & 63));
;         const float2* tp = tab + pos * 16;
; #pragma unroll
;         for (int i = 0; i < 8; ++i) {
;           const float2 cs = tp[crow(i, h)];
;           const float x1 = acc[nb][tb][i], x2 = acc[nb][tb][i + 8];
;           acc[nb][tb][i] = x1 * cs.x - x2 * cs.y;
;           acc[nb][tb][i + 8] = x1 * cs.y + x2 * cs.x;
;         }
;       }
;     }
; #pragma unroll
;     for (int nb = 0; nb < 2; ++nb)
; #pragma unroll
;       for (int g = 0; g < 4; ++g) {
;         uint2 u;
	ds_read_b128 v[66:69], v75 offset:36864
	ds_read_b128 v[70:73], v112 offset:55296
	ds_read_b128 v[76:79], v112 offset:55328
	ds_read_b128 v[84:87], v75 offset:36896
	ds_read_b128 v[88:91], v75 offset:41472
	ds_read_b128 v[92:95], v75 offset:41504
	v_ashrrev_i32_e32 v0, 7, v82
	v_and_b32_e32 v0, 0xffffffe0, v0
	s_waitcnt lgkmcnt(4)
	v_mfma_f32_32x32x16_bf16 v[50:65], v[66:69], v[70:73], v[50:65]
	s_waitcnt lgkmcnt(1)
	v_mfma_f32_32x32x16_bf16 v[34:49], v[88:91], v[70:73], v[34:49]
	ds_read_b128 v[70:73], v112 offset:59904
	ds_read_b128 v[96:99], v112 offset:59936
	v_mfma_f32_32x32x16_bf16 v[50:65], v[84:87], v[76:79], v[50:65]
	s_waitcnt lgkmcnt(2)
	v_mfma_f32_32x32x16_bf16 v[34:49], v[92:95], v[76:79], v[34:49]
	s_waitcnt lgkmcnt(1)
	v_mfma_f32_32x32x16_bf16 v[18:33], v[66:69], v[70:73], v[18:33]
	v_mfma_f32_32x32x16_bf16 v[2:17], v[88:91], v[70:73], v[2:17]
	ds_read_b128 v[76:79], v75 offset:36928
	ds_read_b128 v[70:73], v112 offset:55360
	ds_read_b128 v[88:91], v112 offset:55392
	ds_read_b128 v[100:103], v75 offset:36960
	ds_read_b128 v[104:107], v75 offset:41536
	ds_read_b128 v[66:69], v75 offset:41568
	v_ashrrev_i32_e32 v75, 31, v74
	v_lshlrev_b64 v[80:81], 5, v[74:75]
	v_lshl_add_u64 v[80:81], s[0:1], 0, v[80:81]
	v_or_b32_e32 v74, 32, v74
	v_ashrrev_i32_e32 v75, 31, v74
	s_waitcnt lgkmcnt(4)
	v_mfma_f32_32x32x16_bf16 v[50:65], v[76:79], v[70:73], v[50:65]
	v_lshlrev_b64 v[74:75], 5, v[74:75]
	v_lshl_add_u64 v[74:75], s[0:1], 0, v[74:75]
	s_mov_b64 s[0:1], 0x438
	s_waitcnt lgkmcnt(1)
	v_mfma_f32_32x32x16_bf16 v[34:49], v[104:107], v[70:73], v[34:49]
	ds_read_b128 v[108:111], v112 offset:59968
	ds_read_b128 v[70:73], v112 offset:60000
	s_waitcnt lgkmcnt(0)
	s_barrier
	global_load_dwordx2 v[80:81], v[80:81], off offset:12
	v_mfma_f32_32x32x16_bf16 v[18:33], v[84:87], v[96:99], v[18:33]
	v_or_b32_e32 v85, s34, v83
	v_mov_b32_e32 v84, v228
	v_mfma_f32_32x32x16_bf16 v[18:33], v[76:79], v[108:111], v[18:33]
	global_load_dwordx2 v[76:77], v[74:75], off offset:12
	v_add_u32_e32 v74, s8, v0
	v_lshlrev_b32_e32 v0, 23, v85
	v_lshl_add_u64 v[86:87], s[90:91], 0, v[0:1]
	v_ashrrev_i32_e32 v75, 31, v74
	v_lshrrev_b32_e32 v0, 2, v84
	v_mfma_f32_32x32x16_bf16 v[2:17], v[92:95], v[96:99], v[2:17]
	v_and_b32_e32 v0, 8, v0
	v_lshl_add_u64 v[86:87], v[86:87], 0, v[0:1]
	v_lshl_add_u64 v[74:75], v[74:75], 2, s[86:87]
	v_lshl_add_u64 v[78:79], v[74:75], 0, s[0:1]
	v_cmp_ne_u64_e32 vcc, 0, v[78:79]
	v_and_or_b32 v78, v84, 31, v82
	v_ashrrev_i32_e32 v79, 31, v78
	v_mfma_f32_32x32x16_bf16 v[2:17], v[104:107], v[108:111], v[2:17]
	s_mov_b64 s[0:1], 0x16000000
	s_waitcnt vmcnt(1)
	v_add_f32_e32 v0, v80, v81
	v_mfma_f32_32x32x16_bf16 v[50:65], v[100:103], v[88:91], v[50:65]
	v_fmamk_f32 v0, v0, 0x3c000000, v229
	v_rsq_f32_e32 v0, v0
	v_lshl_add_u64 v[80:81], v[86:87], 0, s[0:1]
	v_mfma_f32_32x32x16_bf16 v[34:49], v[66:69], v[88:91], v[34:49]
	v_lshlrev_b64 v[88:89], 7, v[78:79]
	v_lshl_add_u64 v[86:87], v[80:81], 0, v[88:89]
	s_nop 5
	v_mul_f32_e64 v88, v50, v0
	v_mul_f32_e64 v89, v51, v0
	v_mul_f32_e64 v90, v52, v0
	v_mul_f32_e64 v91, v53, v0
	v_pk_mul_f32 v[92:93], v[54:55], v[0:1] op_sel_hi:[1,0]
	v_pk_mul_f32 v[94:95], v[56:57], v[0:1] op_sel_hi:[1,0]
	v_pk_mul_f32 v[96:97], v[58:59], v[0:1] op_sel_hi:[1,0]
	v_mfma_f32_32x32x16_bf16 v[18:33], v[100:103], v[70:73], v[18:33]
	v_mul_f32_e64 v98, v60, v0
	v_mul_f32_e64 v99, v61, v0
	v_mul_f32_e64 v100, v62, v0
	v_mul_f32_e64 v101, v63, v0
	v_mul_f32_e64 v102, v64, v0
	v_mul_f32_e64 v103, v65, v0
	v_pk_mul_f32 v[104:105], v[34:35], v[0:1] op_sel_hi:[1,0]
	v_pk_mul_f32 v[106:107], v[36:37], v[0:1] op_sel_hi:[1,0]
	v_pk_mul_f32 v[108:109], v[38:39], v[0:1] op_sel_hi:[1,0]
	v_pk_mul_f32 v[110:111], v[40:41], v[0:1] op_sel_hi:[1,0]
	v_mfma_f32_32x32x16_bf16 v[2:17], v[66:69], v[70:73], v[2:17]
	v_mul_f32_e64 v112, v42, v0
	v_mul_f32_e64 v113, v43, v0
	v_mul_f32_e64 v114, v44, v0
	v_mul_f32_e64 v115, v45, v0
	v_mul_f32_e64 v116, v46, v0
	v_mul_f32_e64 v117, v47, v0
	v_pk_mul_f32 v[118:119], v[48:49], v[0:1] op_sel_hi:[1,0]
	v_cvt_pk_bf16_f32 v66, v88, v89
	v_cvt_pk_bf16_f32 v67, v90, v91
	v_cvt_pk_bf16_f32 v68, v92, v93
	v_cvt_pk_bf16_f32 v69, v94, v95
	v_cvt_pk_bf16_f32 v70, v96, v97
	v_cvt_pk_bf16_f32 v71, v98, v99
	v_cvt_pk_bf16_f32 v72, v100, v101
	v_cvt_pk_bf16_f32 v73, v102, v103
	v_cvt_pk_bf16_f32 v88, v104, v105
	v_cvt_pk_bf16_f32 v89, v106, v107
	v_cvt_pk_bf16_f32 v90, v108, v109
	v_cvt_pk_bf16_f32 v91, v110, v111
	v_cvt_pk_bf16_f32 v92, v112, v113
	v_cvt_pk_bf16_f32 v93, v114, v115
	v_cvt_pk_bf16_f32 v94, v116, v117
	v_cvt_pk_bf16_f32 v95, v118, v119
	v_and_b32_e32 v96, 32, v228
	v_lshrrev_b32_e32 v96, 2, v96
	v_mov_b32_e32 v97, 0
	v_lshl_add_u64 v[98:99], v[86:87], 0, v[96:97]
	v_permlane32_swap_b32_e32 v66, v68
	v_permlane32_swap_b32_e32 v67, v69
	v_permlane32_swap_b32_e32 v70, v72
	v_permlane32_swap_b32_e32 v71, v73
	v_permlane32_swap_b32_e32 v88, v90
	v_permlane32_swap_b32_e32 v89, v91
	v_permlane32_swap_b32_e32 v92, v94
	v_permlane32_swap_b32_e32 v93, v95
	global_store_dwordx4 v[98:99], v[66:69], off
	global_store_dwordx4 v[98:99], v[70:73], off offset:32
	global_store_dwordx4 v[98:99], v[88:91], off offset:64
	global_store_dwordx4 v[98:99], v[92:95], off offset:96
	s_nop 1
	v_mov_b32_e32 v66, 0
	s_and_saveexec_b64 s[6:7], vcc
	s_cbranch_execz .LBB0_567
	v_mul_f32_e32 v51, v51, v51
	v_fmac_f32_e32 v51, v50, v50
	v_fmac_f32_e32 v51, v52, v52
	v_fmac_f32_e32 v51, v53, v53
	v_fmac_f32_e32 v51, v54, v54
	v_fmac_f32_e32 v51, v55, v55
	v_fmac_f32_e32 v51, v56, v56
	v_fmac_f32_e32 v51, v57, v57
	v_fmac_f32_e32 v51, v58, v58
	v_fmac_f32_e32 v51, v59, v59
	v_fmac_f32_e32 v51, v60, v60
	v_fmac_f32_e32 v51, v61, v61
	v_fmac_f32_e32 v51, v62, v62
	v_fmac_f32_e32 v51, v63, v63
	v_fmac_f32_e32 v51, v64, v64
	v_fmac_f32_e32 v51, v65, v65
	v_fmac_f32_e32 v51, v34, v34
	v_fmac_f32_e32 v51, v35, v35
	v_fmac_f32_e32 v51, v36, v36
	v_fmac_f32_e32 v51, v37, v37
	v_fmac_f32_e32 v51, v38, v38
	v_fmac_f32_e32 v51, v39, v39
	v_fmac_f32_e32 v51, v40, v40
	v_fmac_f32_e32 v51, v41, v41
	v_pk_mul_f32 v[40:41], v[42:43], v[42:43]
	v_pk_mul_f32 v[38:39], v[44:45], v[44:45]
	v_add_f32_e32 v40, v40, v51
	v_add_f32_e32 v40, v41, v40
	v_add_f32_e32 v38, v38, v40
	v_pk_mul_f32 v[36:37], v[46:47], v[46:47]
	v_add_f32_e32 v38, v39, v38
	v_add_f32_e32 v36, v36, v38
	v_pk_mul_f32 v[34:35], v[48:49], v[48:49]
	v_add_f32_e32 v36, v37, v36
	v_add_f32_e32 v34, v34, v36
	v_cmp_lt_i32_e64 s[0:1], v234, v233
	v_add_f32_e32 v34, v35, v34
	s_nop 0
	v_cndmask_b32_e64 v35, v232, v234, s[0:1]
	v_lshlrev_b32_e32 v35, 2, v35
	ds_bpermute_b32 v35, v35, v34
	s_waitcnt lgkmcnt(0)
	v_add_f32_e32 v34, v34, v35
	v_mul_f32_e32 v34, v0, v34
	v_mul_f32_e32 v0, v0, v34
	v_max_f32_e32 v66, 0, v0
; DI float frsq(float x) { return __builtin_amdgcn_rsqf(x); }
; DI int crow(int i, int h) { return (i & 3) + 8 * (i >> 2) + 4 * h; }
; DI void epi_slot(f32x16 (&acc)[2][2], bf16_t* dst  , int tok0  , const float* norm_gain,
;                  int rope, const float2* tab, float* ssq_out, const float (&rs)[2], unsigned* kmax_out = nullptr) {
;     ...
;   for (int tb = 0; tb < 2; ++tb) {
;     const int tok = tok0 + tb * 32 + r;
;     float sc = rs[tb];
;     if (norm_gain || ssq_out) {
;       float ss = 0.f;
; #pragma unroll
;       for (int nb = 0; nb < 2; ++nb)
; #pragma unroll
;         for (int i = 0; i < 16; ++i) ss += acc[nb][tb][i] * acc[nb][tb][i];
;       ss += xhalf(ss);
;       if (ssq_out && h == 0) ssq_out[(size_t)tok * 8] = ss;
;       if (norm_gain) {
;         const float rstd = frsq(ss * (1.f / 64.f) + EPS);
; #pragma unroll
;         for (int nb = 0; nb < 2; ++nb)
; #pragma unroll
;           for (int i = 0; i < 16; ++i) acc[nb][tb][i] *= rstd * norm_gain[nb * 32 + crow(i, h)];
;       }
;     }
;     if (rope) {
;       const int s = tok & (SEQ - 1);
; #pragma unroll
;       for (int nb = 0; nb < 2; ++nb) {
;         const int pos = (rope == 2) ? s : (nb == 0 ? (s >> 6) : (s & 63));
;         const float2* tp = tab + pos * 16;
; #pragma unroll
;         for (int i = 0; i < 8; ++i) {
;           const float2 cs = tp[crow(i, h)];
;           const float x1 = acc[nb][tb][i], x2 = acc[nb][tb][i + 8];
;           acc[nb][tb][i] = x1 * cs.x - x2 * cs.y;
;           acc[nb][tb][i + 8] = x1 * cs.y + x2 * cs.x;
;         }
;       }
;     }
; #pragma unroll
;     for (int nb = 0; nb < 2; ++nb)
; #pragma unroll
;       for (int g = 0; g < 4; ++g) {
;         uint2 u;
;         u.x = pk_bf16(acc[nb][tb][4 * g] * sc, acc[nb][tb][4 * g + 1] * sc);
;         u.y = pk_bf16(acc[nb][tb][4 * g + 2] * sc, acc[nb][tb][4 * g + 3] * sc);
;         *(uint2*)(dst + (size_t)tok * 64 + nb * 32 + 8 * g + 4 * h) = u;
;       }
;     if (kmax_out) {
;       float ss = 0.f;
; #pragma unroll
;       for (int nb = 0; nb < 2; ++nb)
; #pragma unroll
;         for (int i = 0; i < 16; ++i) ss += acc[nb][tb][i] * acc[nb][tb][i];
;       ss += xhalf(ss);
;       kmx = fmaxf(kmx, ss * sc * sc);
;     }
;   }
;   if (kmax_out) {
; #pragma unroll
;     for (int o = 1; o < 32; o <<= 1) kmx = fmaxf(kmx, __shfl_xor(kmx, o));
;     if (lane == 0) atomic_max_pos(kmax_out, kmx);
;   }
.LBB0_567:
	s_or_b64 exec, exec, s[6:7]
	s_waitcnt vmcnt(4)
	v_add_f32_e32 v0, v76, v77
	v_fmamk_f32 v0, v0, 0x3c000000, v229
	v_rsq_f32_e32 v0, v0
	v_or_b32_e32 v34, 32, v78
	v_ashrrev_i32_e32 v35, 31, v34
	v_lshlrev_b64 v[34:35], 7, v[34:35]
	v_lshl_add_u64 v[34:35], v[80:81], 0, v[34:35]
	v_pk_mul_f32 v[36:37], v[0:1], v[18:19] op_sel_hi:[0,1]
	v_pk_mul_f32 v[38:39], v[0:1], v[20:21] op_sel_hi:[0,1]
	v_cvt_pk_bf16_f32 v88, v36, v37
	v_cvt_pk_bf16_f32 v89, v38, v39
	v_pk_mul_f32 v[36:37], v[0:1], v[22:23] op_sel_hi:[0,1]
	v_pk_mul_f32 v[38:39], v[0:1], v[24:25] op_sel_hi:[0,1]
	v_cvt_pk_bf16_f32 v90, v36, v37
	v_cvt_pk_bf16_f32 v91, v38, v39
	v_pk_mul_f32 v[36:37], v[0:1], v[26:27] op_sel_hi:[0,1]
	v_pk_mul_f32 v[38:39], v[0:1], v[28:29] op_sel_hi:[0,1]
	v_cvt_pk_bf16_f32 v92, v36, v37
	v_cvt_pk_bf16_f32 v93, v38, v39
	v_pk_mul_f32 v[36:37], v[0:1], v[30:31] op_sel_hi:[0,1]
	v_pk_mul_f32 v[38:39], v[0:1], v[32:33] op_sel_hi:[0,1]
	v_cvt_pk_bf16_f32 v94, v36, v37
	v_cvt_pk_bf16_f32 v95, v38, v39
	v_pk_mul_f32 v[36:37], v[0:1], v[2:3] op_sel_hi:[0,1]
	v_pk_mul_f32 v[38:39], v[0:1], v[4:5] op_sel_hi:[0,1]
	v_cvt_pk_bf16_f32 v96, v36, v37
	v_cvt_pk_bf16_f32 v97, v38, v39
	v_pk_mul_f32 v[36:37], v[0:1], v[6:7] op_sel_hi:[0,1]
	v_pk_mul_f32 v[38:39], v[0:1], v[8:9] op_sel_hi:[0,1]
	v_cvt_pk_bf16_f32 v98, v36, v37
	v_cvt_pk_bf16_f32 v99, v38, v39
	v_pk_mul_f32 v[36:37], v[0:1], v[10:11] op_sel_hi:[0,1]
	v_pk_mul_f32 v[38:39], v[0:1], v[12:13] op_sel_hi:[0,1]
	v_cvt_pk_bf16_f32 v100, v36, v37
	v_cvt_pk_bf16_f32 v101, v38, v39
	v_pk_mul_f32 v[36:37], v[0:1], v[14:15] op_sel_hi:[0,1]
	v_pk_mul_f32 v[38:39], v[0:1], v[16:17] op_sel_hi:[0,1]
	v_cvt_pk_bf16_f32 v102, v36, v37
	v_cvt_pk_bf16_f32 v103, v38, v39
	v_and_b32_e32 v104, 32, v228
	v_lshrrev_b32_e32 v104, 2, v104
	v_mov_b32_e32 v105, 0
	v_lshl_add_u64 v[106:107], v[34:35], 0, v[104:105]
	v_permlane32_swap_b32_e32 v88, v90
	v_permlane32_swap_b32_e32 v89, v91
	v_permlane32_swap_b32_e32 v92, v94
	v_permlane32_swap_b32_e32 v93, v95
	v_permlane32_swap_b32_e32 v96, v98
	v_permlane32_swap_b32_e32 v97, v99
	v_permlane32_swap_b32_e32 v100, v102
	v_permlane32_swap_b32_e32 v101, v103
	global_store_dwordx4 v[106:107], v[88:91], off
	global_store_dwordx4 v[106:107], v[92:95], off offset:32
	global_store_dwordx4 v[106:107], v[96:99], off offset:64
	global_store_dwordx4 v[106:107], v[100:103], off offset:96
	s_nop 1
	s_and_saveexec_b64 s[0:1], vcc
	s_cbranch_execz .LBB0_570
	v_mul_f32_e32 v19, v19, v19
	v_fmac_f32_e32 v19, v18, v18
	v_fmac_f32_e32 v19, v20, v20
	v_fmac_f32_e32 v19, v21, v21
	v_fmac_f32_e32 v19, v22, v22
	v_fmac_f32_e32 v19, v23, v23
	v_fmac_f32_e32 v19, v24, v24
	v_fmac_f32_e32 v19, v25, v25
	v_fmac_f32_e32 v19, v26, v26
	v_fmac_f32_e32 v19, v27, v27
	v_fmac_f32_e32 v19, v28, v28
	v_fmac_f32_e32 v19, v29, v29
	v_fmac_f32_e32 v19, v30, v30
	v_fmac_f32_e32 v19, v31, v31
	v_fmac_f32_e32 v19, v32, v32
	v_fmac_f32_e32 v19, v33, v33
	v_fmac_f32_e32 v19, v2, v2
	v_fmac_f32_e32 v19, v3, v3
	v_fmac_f32_e32 v19, v4, v4
	v_fmac_f32_e32 v19, v5, v5
	v_fmac_f32_e32 v19, v6, v6
	v_fmac_f32_e32 v19, v7, v7
	v_fmac_f32_e32 v19, v8, v8
	v_fmac_f32_e32 v19, v9, v9
	v_fmac_f32_e32 v19, v10, v10
	v_fmac_f32_e32 v19, v11, v11
	v_fmac_f32_e32 v19, v12, v12
	v_fmac_f32_e32 v19, v13, v13
	v_fmac_f32_e32 v19, v14, v14
	v_fmac_f32_e32 v19, v15, v15
	v_cmp_lt_i32_e32 vcc, v234, v233
	v_fmac_f32_e32 v19, v16, v16
	v_fmac_f32_e32 v19, v17, v17
	v_cndmask_b32_e32 v2, v232, v234, vcc
	v_lshlrev_b32_e32 v2, 2, v2
	ds_bpermute_b32 v2, v2, v19
	v_cmp_lt_i32_e32 vcc, v250, v233
	v_max_f32_e32 v3, v66, v66
	s_waitcnt lgkmcnt(0)
	v_add_f32_e32 v2, v19, v2
	v_mul_f32_e32 v2, v0, v2
	v_mul_f32_e32 v0, v0, v2
	v_cndmask_b32_e32 v2, v232, v250, vcc
	v_max_f32_e32 v0, v3, v0
	v_lshlrev_b32_e32 v2, 2, v2
	ds_bpermute_b32 v2, v2, v0
	v_xor_b32_e32 v3, 4, v232
	s_waitcnt lgkmcnt(0)
	v_max_f32_e32 v2, v2, v2
	v_max_f32_e32 v0, v0, v2
	v_xor_b32_e32 v2, 2, v232
	v_cmp_lt_i32_e32 vcc, v2, v233
	s_nop 1
	v_cndmask_b32_e32 v2, v232, v2, vcc
	v_lshlrev_b32_e32 v2, 2, v2
	ds_bpermute_b32 v2, v2, v0
	v_cmp_lt_i32_e32 vcc, v3, v233
	s_waitcnt lgkmcnt(0)
	v_max_f32_e32 v2, v2, v2
	v_cndmask_b32_e32 v3, v232, v3, vcc
	v_max_f32_e32 v0, v0, v2
	v_lshlrev_b32_e32 v2, 2, v3
	ds_bpermute_b32 v2, v2, v0
	v_xor_b32_e32 v3, 8, v232
	v_cmp_lt_i32_e32 vcc, v3, v233
	s_waitcnt lgkmcnt(0)
	v_max_f32_e32 v2, v2, v2
	v_cndmask_b32_e32 v3, v232, v3, vcc
	v_lshlrev_b32_e32 v3, 2, v3
	v_max_f32_e32 v0, v0, v2
	ds_bpermute_b32 v2, v3, v0
	v_cmp_lt_i32_e32 vcc, v235, v233
	s_waitcnt lgkmcnt(0)
	v_max_f32_e32 v2, v2, v2
	v_cndmask_b32_e32 v3, v232, v235, vcc
	v_max_f32_e32 v2, v0, v2
	v_lshlrev_b32_e32 v0, 2, v3
	ds_bpermute_b32 v3, v0, v2
	v_and_b32_e32 v0, 63, v84
	v_cmp_eq_u32_e32 vcc, 0, v0
	s_and_b64 exec, exec, vcc
	s_cbranch_execz .LBB0_570
	s_lshl_b32 s34, s34, 2
	v_lshl_add_u64 v[4:5], v[74:75], 0, s[34:35]
	v_lshlrev_b32_e32 v0, 2, v83
	v_lshl_add_u64 v[4:5], v[4:5], 0, v[0:1]
	s_waitcnt lgkmcnt(0)
	v_max_f32_e32 v0, v3, v3
	v_max_f32_e32 v2, v2, v2
	v_max_f32_e32 v0, v2, v0
	global_atomic_umax v[4:5], v0, off offset:1080
